# out-projection (layer 0): slice-first unit order as well
# baseline (speedup 1.0000x reference)
.LBB0_1248:
	s_cmp_gt_u32 s76, 256
	s_cbranch_scc1 .Lrm3_p_done
	v_readlane_b32 s84, v254, 2
	s_cmp_lg_u32 s84, 320
	s_cbranch_scc1 .Lrm3_p_done
	s_cmp_lt_u32 s75, 64
	s_cbranch_scc0 .Lrm3_p_done
	s_lshr_b32 s84, s75, 2
	s_lshr_b32 s6, s84, 2
	s_add_u32 s6, s6, 64
	s_and_b32 s4, s84, 3
	s_and_b32 s30, s75, 3
	s_lshl_b32 s30, s30, 2
	s_mov_b32 s74, 4

.LBB0_1254:
	s_add_i32 s72, s72, 1
	v_readlane_b32 s5, v253, 10
	s_mul_i32 s5, s72, s5
	s_mul_hi_u32 s7, s72, s76
	s_add_i32 s7, s7, s5
	s_mul_i32 s5, s72, s76
	v_readlane_b32 s8, v254, 2
	s_add_u32 s26, s5, s75
	v_readlane_b32 s5, v253, 9
	v_readlane_b32 s9, v254, 3
	s_addc_u32 s27, s7, s5
	s_cmp_gt_u32 s76, 256
	s_cbranch_scc1 .Lrm3_done
	s_cmp_lg_u32 s8, 320
	s_cbranch_scc1 .Lrm3_done
	s_cmp_lg_u32 s27, 0
	s_cbranch_scc1 .Lrm3_done
	s_cmp_ge_u32 s26, 320
	s_cbranch_scc1 .Lrm3_done
	s_cmp_lt_u32 s26, 64
	s_cbranch_scc1 .Lrm3_add
	s_cmp_lt_u32 s26, 256
	s_cbranch_scc1 .Lrm3_done
	s_sub_u32 s26, s26, 256
	s_branch .Lrm3_done
.Lrm3_add:
	s_add_u32 s26, s26, 256
.Lrm3_done:
	s_waitcnt lgkmcnt(0)
	v_mov_b64_e32 v[2:3], s[8:9]
	v_cmp_ge_i64_e32 vcc, s[26:27], v[2:3]
	v_cmp_lt_i64_e64 s[8:9], s[26:27], v[2:3]
	s_cbranch_vccnz .LBB0_1263
	v_cmp_lt_i64_e32 vcc, s[26:27], v[146:147]
	s_mov_b64 s[28:29], -1
	s_cbranch_vccnz .LBB0_1257
	s_add_i32 s5, s26, 0xffffff00
	s_ashr_i32 s7, s5, 31
	s_lshr_b32 s20, s7, 30
	s_add_i32 s20, s5, s20
	s_ashr_i32 s21, s20, 2
	s_and_b32 s20, s20, 0x3ffffffc
	s_lshr_b32 s7, s7, 28
	s_sub_i32 s20, s5, s20
	s_add_i32 s5, s5, s7
	s_ashr_i32 s5, s5, 4
	s_add_i32 s22, s5, 64
	s_lshr_b32 s5, s21, 30
	s_add_i32 s5, s21, s5
	s_and_b32 s5, s5, -4
	s_sub_i32 s24, s21, s5
	s_lshl_b32 s20, s20, 2
	s_mov_b64 s[28:29], 0
